# barrier poll back-off s_sleep 16 stacked on v56
# baseline (speedup 1.0000x reference)
.LBB0_134:
	s_and_b32 s2, s0, 0xff
	s_mov_b64 s[36:37], -1
	s_cmp_lg_u32 s2, 0
	s_mov_b64 s[42:43], -1
	s_sleep 16
	s_cbranch_scc1 .LBB0_137
	v_readlane_b32 s14, v251, 4
	v_readlane_b32 s15, v251, 5
	s_nop 4
	global_load_dword v2, v1, s[14:15] sc1
	s_waitcnt vmcnt(0)
	v_cmp_eq_u32_e32 vcc, 0, v2
	s_cbranch_vccnz .LBB0_139
	s_mov_b64 s[42:43], 0
	s_mov_b64 s[38:39], -1

.LBB0_520:
	s_and_b32 s2, s0, 0xff
	s_mov_b64 s[36:37], -1
	s_cmp_lg_u32 s2, 0
	s_mov_b64 s[44:45], -1
	s_sleep 16
	s_cbranch_scc1 .LBB0_523
	v_readlane_b32 s14, v251, 4
	v_readlane_b32 s15, v251, 5
	s_nop 4
	global_load_dword v2, v1, s[14:15] sc1
	s_waitcnt vmcnt(0)
	v_cmp_eq_u32_e32 vcc, 0, v2
	s_cbranch_vccnz .LBB0_525
	s_mov_b64 s[44:45], 0
	s_mov_b64 s[38:39], -1
